# ML consumer: counted vmcnt(32) before register rotation (wait for V prefetch loads only, not the h stores)
# baseline (speedup 1.0000x reference)
; #define MFMA32(a, b, c) __builtin_amdgcn_mfma_f32_32x32x16_bf16((a), (b), (c), 0, 0, 0)
; template <bool CONS>
; DI void ml_chain_role(const Params& p, unsigned char* smem, int dir, int b, int h) {
;     ...
; #pragma unroll
;             for (int kt = 0; kt < 4; ++kt) for (int i = 0; i < 16; ++i) C[kt][i] *= cs;
; #pragma unroll
;             for (int ci = 0; ci < 2; ++ci)
; #pragma unroll
;                 for (int s = 0; s < 2; ++s)
; #pragma unroll
;                     for (int kt = 0; kt < 4; ++kt) C[kt] = MFMA32(load_nat(sKT, STT, 32 * kt + r, 32 * ci + 16 * s + 8 * hh), vf[ci][s], C[kt]);
;         }
;         if (CONS) __builtin_amdgcn_s_setprio(0);
.LBB0_479:
	s_nop 7
	v_add3_u32 v84, s40, v167, v168
	s_nop 0
	ds_read_b128 v[64:67], v84
	ds_read_b128 v[68:71], v84 offset:32
	ds_read_b128 v[72:75], v84 offset:4608
	s_waitcnt lgkmcnt(3)
	v_pk_mul_f32 v[62:63], v[62:63], v[114:115] op_sel_hi:[1,0]
	v_pk_mul_f32 v[60:61], v[60:61], v[114:115] op_sel_hi:[1,0]
	v_pk_mul_f32 v[58:59], v[58:59], v[114:115] op_sel_hi:[1,0]
	v_pk_mul_f32 v[56:57], v[56:57], v[114:115] op_sel_hi:[1,0]
	v_pk_mul_f32 v[54:55], v[54:55], v[114:115] op_sel_hi:[1,0]
	v_pk_mul_f32 v[52:53], v[52:53], v[114:115] op_sel_hi:[1,0]
	v_pk_mul_f32 v[50:51], v[50:51], v[114:115] op_sel_hi:[1,0]
	v_pk_mul_f32 v[48:49], v[48:49], v[114:115] op_sel_hi:[1,0]
	v_pk_mul_f32 v[46:47], v[46:47], v[114:115] op_sel_hi:[1,0]
	v_pk_mul_f32 v[44:45], v[44:45], v[114:115] op_sel_hi:[1,0]
	v_pk_mul_f32 v[42:43], v[42:43], v[114:115] op_sel_hi:[1,0]
	v_pk_mul_f32 v[40:41], v[40:41], v[114:115] op_sel_hi:[1,0]
	v_pk_mul_f32 v[38:39], v[38:39], v[114:115] op_sel_hi:[1,0]
	v_pk_mul_f32 v[36:37], v[36:37], v[114:115] op_sel_hi:[1,0]
	v_pk_mul_f32 v[34:35], v[34:35], v[114:115] op_sel_hi:[1,0]
	v_pk_mul_f32 v[32:33], v[32:33], v[114:115] op_sel_hi:[1,0]
	s_waitcnt lgkmcnt(2)
	v_mfma_f32_32x32x16_bf16 v[48:63], v[64:67], v[96:99], v[48:63]
	ds_read_b128 v[64:67], v84 offset:9216
	ds_read_b128 v[76:79], v84 offset:4640
	v_mul_f32_e64 v30, v30, v114
	v_mul_f32_e64 v31, v31, v114
	v_mul_f32_e64 v28, v28, v114
	v_mul_f32_e64 v29, v29, v114
	v_pk_mul_f32 v[26:27], v[26:27], v[114:115] op_sel_hi:[1,0]
	v_pk_mul_f32 v[24:25], v[24:25], v[114:115] op_sel_hi:[1,0]
	v_pk_mul_f32 v[22:23], v[22:23], v[114:115] op_sel_hi:[1,0]
	v_pk_mul_f32 v[20:21], v[20:21], v[114:115] op_sel_hi:[1,0]
	s_waitcnt lgkmcnt(2)
	v_mfma_f32_32x32x16_bf16 v[32:47], v[72:75], v[96:99], v[32:47]
	ds_read_b128 v[72:75], v84 offset:13824
	ds_read_b128 v[80:83], v84 offset:9248
	v_mul_f32_e64 v18, v18, v114
	v_mul_f32_e64 v19, v19, v114
	v_mul_f32_e64 v16, v16, v114
	v_mul_f32_e64 v17, v17, v114
	v_pk_mul_f32 v[14:15], v[14:15], v[114:115] op_sel_hi:[1,0]
	v_pk_mul_f32 v[12:13], v[12:13], v[114:115] op_sel_hi:[1,0]
	v_pk_mul_f32 v[10:11], v[10:11], v[114:115] op_sel_hi:[1,0]
	v_pk_mul_f32 v[8:9], v[8:9], v[114:115] op_sel_hi:[1,0]
	s_waitcnt lgkmcnt(3)
	v_mfma_f32_32x32x16_bf16 v[16:31], v[64:67], v[96:99], v[16:31]
	v_mul_f32_e64 v6, v6, v114
	v_mul_f32_e64 v7, v7, v114
	v_mul_f32_e64 v4, v4, v114
	v_mul_f32_e64 v5, v5, v114
	v_mul_f32_e64 v2, v2, v114
	v_mul_f32_e64 v3, v3, v114
	v_pk_mul_f32 v[0:1], v[0:1], v[114:115] op_sel_hi:[1,0]
	ds_read_b128 v[64:67], v84 offset:13856
	s_waitcnt lgkmcnt(2)
	v_mfma_f32_32x32x16_bf16 v[0:15], v[72:75], v[96:99], v[0:15]
	v_mfma_f32_32x32x16_bf16 v[48:63], v[68:71], v[104:107], v[48:63]
	v_mfma_f32_32x32x16_bf16 v[32:47], v[76:79], v[104:107], v[32:47]
	s_waitcnt lgkmcnt(0)
	v_mfma_f32_32x32x16_bf16 v[0:15], v[64:67], v[104:107], v[0:15]
	ds_read_b128 v[64:67], v84 offset:64
	ds_read_b128 v[68:71], v84 offset:96
	v_mfma_f32_32x32x16_bf16 v[16:31], v[80:83], v[104:107], v[16:31]
	s_waitcnt lgkmcnt(1)
	v_mfma_f32_32x32x16_bf16 v[48:63], v[64:67], v[100:103], v[48:63]
	ds_read_b128 v[64:67], v84 offset:4672
	ds_read_b128 v[72:75], v84 offset:4704
	s_waitcnt lgkmcnt(1)
	v_mfma_f32_32x32x16_bf16 v[32:47], v[64:67], v[100:103], v[32:47]
	ds_read_b128 v[64:67], v84 offset:9280
	ds_read_b128 v[76:79], v84 offset:9312
	s_waitcnt lgkmcnt(1)
	v_mfma_f32_32x32x16_bf16 v[16:31], v[64:67], v[100:103], v[16:31]
	ds_read_b128 v[64:67], v84 offset:13888
	ds_read_b128 v[80:83], v84 offset:13920
	s_waitcnt lgkmcnt(1)
	v_mfma_f32_32x32x16_bf16 v[0:15], v[64:67], v[100:103], v[0:15]
	v_mfma_f32_32x32x16_bf16 v[48:63], v[68:71], v[108:111], v[48:63]
	v_mfma_f32_32x32x16_bf16 v[32:47], v[72:75], v[108:111], v[32:47]
	v_mfma_f32_32x32x16_bf16 v[16:31], v[76:79], v[108:111], v[16:31]
	s_waitcnt lgkmcnt(0)
	v_mfma_f32_32x32x16_bf16 v[0:15], v[80:83], v[108:111], v[0:15]
	s_setprio 0
	s_cmp_eq_u32 s86, 0
	s_cbranch_scc1 .Lmlw_all
	s_waitcnt vmcnt(32)
	s_branch .Lmlw_done

; template <bool CONS>
; DI void ml_chain_role(const Params& p, unsigned char* smem, int dir, int b, int h) {
;     ...
;             for (int ci = 0; ci < 2; ++ci)
; #pragma unroll
;                 for (int s = 0; s < 2; ++s)
; #pragma unroll
;                     for (int e = 0; e < 8; ++e) vf[ci][s][e] = (short)pvv[ci][s][e];
.Lmlw_done:
	s_add_i32 s25, s25, 1
	s_addk_i32 s9, 0x1000
	s_cmpk_eq_i32 s25, 0x41
	v_mov_b32_e32 v163, v149
	v_mov_b32_e32 v164, v148
	v_mov_b32_e32 v161, v147
	v_mov_b32_e32 v162, v146
	v_mov_b32_e32 v159, v145
	v_mov_b32_e32 v160, v144
	v_mov_b32_e32 v157, v143
	v_mov_b32_e32 v158, v142
	v_mov_b32_e32 v155, v141
	v_mov_b32_e32 v156, v140
	v_mov_b32_e32 v153, v139
	v_mov_b32_e32 v154, v138
	v_mov_b32_e32 v151, v137
	v_mov_b32_e32 v152, v136
	v_mov_b32_e32 v114, v135
	v_mov_b32_e32 v150, v134
	v_mov_b32_e32 v106, v133
	v_mov_b32_e32 v107, v132
	v_mov_b32_e32 v104, v131
	v_mov_b32_e32 v105, v130
	v_mov_b32_e32 v102, v129
	v_mov_b32_e32 v103, v128
	v_mov_b32_e32 v100, v127
	v_mov_b32_e32 v101, v126
	v_mov_b32_e32 v99, v125
	v_mov_b32_e32 v111, v124
	v_mov_b32_e32 v98, v123
	v_mov_b32_e32 v110, v122
	v_mov_b32_e32 v97, v121
	v_mov_b32_e32 v109, v120
	v_mov_b32_e32 v96, v119
	v_mov_b32_e32 v108, v118
	s_cbranch_scc1 .LBB0_494

; template <bool CONS>
; DI void ml_chain_role(const Params& p, unsigned char* smem, int dir, int b, int h) {
;     ...
;         } else {
; #pragma unroll
;             for (int mi = 0; mi < 2; ++mi) for (int i = 0; i < 16; ++i) o[mi][i] = 0.f;
; #pragma unroll
;             for (int kt = 0; kt < 4; ++kt)
; #pragma unroll
;                 for (int s = 0; s < 2; ++s) { const bf16x8 bf = pack_step(C[kt], s);
; #pragma unroll
;                     for (int mi = 0; mi < 2; ++mi) o[mi] = MFMA32(load_perm(sQ, ST, 32 * mi + r, 32 * kt + 16 * s, hh), bf, o[mi]); }
; #pragma unroll
;             for (int mi = 0; mi < 2; ++mi)
; #pragma unroll
;                 for (int i = 0; i < 16; ++i) o[mi][i] *= sWin[32 * mi + crow(i, hh)];
;         }
;         LDS_BARRIER();
;         if (!CONS) {
;             const int t = tid - 256;
;             { const int i = t >> 2, part = t & 3; float qn = 0.f, rs = 0.f;
; #pragma unroll
;               for (int q = 0; q < 4; ++q) { const u32x4 qv = *(const u32x4*)(sQ + i * ST + part * 32 + 8 * q);
;                   const f32x4 n0 = *(const f32x4*)(sN + part * 32 + 8 * q), n1 = *(const f32x4*)(sN + part * 32 + 8 * q + 4);
;                   qn += (bflo(qv.x) * n0.x + bfhi(qv.x) * n0.y) + (bflo(qv.y) * n0.z + bfhi(qv.y) * n0.w) + (bflo(qv.z) * n1.x + bfhi(qv.z) * n1.y) + (bflo(qv.w) * n1.z + bfhi(qv.w) * n1.w); }
; #pragma unroll
;               for (int q = 0; q < 2; ++q) { const u32x4 sv = *(const u32x4*)(sS + i * STT + part * 16 + 8 * q);
;                   rs += (bflo(sv.x) + bfhi(sv.x)) + (bflo(sv.y) + bfhi(sv.y)) + (bflo(sv.z) + bfhi(sv.z)) + (bflo(sv.w) + bfhi(sv.w)); }
;               qn += __shfl_xor(qn, 1); qn += __shfl_xor(qn, 2); rs += __shfl_xor(rs, 1); rs += __shfl_xor(rs, 2);
;               if (part == 0) { const float den = sWin[i] * qn + rs; sRden[i] = 1.f / fmaxf(fabsf(den), sFloor[i]); } }
;             if (wave < 6) {
;                 const int k = t; float acc = sCs[0] * sN[k];
; #pragma unroll
;                 for (int q = 0; q < 8; ++q) { const u32x4 kv = *(const u32x4*)(sKT + k * STT + 8 * q);
;                     acc += (bflo(kv.x) + bfhi(kv.x)) + (bflo(kv.y) + bfhi(kv.y)) + (bflo(kv.z) + bfhi(kv.z)) + (bflo(kv.w) + bfhi(kv.w)); }
;                 sNw[k] = acc;
;             }
;             __builtin_amdgcn_s_setprio(0);
;         } else {
; #pragma unroll
;             for (int ci = 0; ci < 2; ++ci)
.LBB0_492:
	v_mul_u32_u24_e32 v65, 0x110, v165
	s_waitcnt lgkmcnt(0)
	s_barrier
	v_add3_u32 v112, 0, v64, v65
	ds_read2_b64 v[64:67], v112 offset1:2
	v_cvt_pk_bf16_f32 v68, v48, v49
	v_cvt_pk_bf16_f32 v69, v50, v51
	v_cvt_pk_bf16_f32 v70, v52, v53
	v_cvt_pk_bf16_f32 v71, v54, v55
	v_add_u32_e32 v176, 0x2000, v112
	ds_read2_b64 v[168:171], v112 offset0:4 offset1:6
	s_waitcnt lgkmcnt(1)
	v_mfma_f32_32x32x16_bf16 v[80:95], v[64:67], v[68:71], 0
	ds_read2_b64 v[64:67], v176 offset0:64 offset1:66
	v_cvt_pk_bf16_f32 v172, v56, v57
	v_cvt_pk_bf16_f32 v173, v58, v59
	v_cvt_pk_bf16_f32 v174, v60, v61
	v_cvt_pk_bf16_f32 v175, v62, v63
	s_and_b32 s14, s9, 0x1000
	s_add_i32 s14, s14, 0
	s_waitcnt lgkmcnt(1)
	v_mfma_f32_32x32x16_bf16 v[80:95], v[168:171], v[172:175], v[80:95]
	ds_read2_b64 v[168:171], v176 offset0:68 offset1:70
	s_add_i32 s14, s14, 0x24400
	v_lshlrev_b32_e32 v167, 4, v167
	v_perm_b32 v99, v99, v111, s39
	v_perm_b32 v98, v98, v110, s39
	v_perm_b32 v97, v97, v109, s39
	v_perm_b32 v96, v96, v108, s39
	s_waitcnt lgkmcnt(1)
	v_mfma_f32_32x32x16_bf16 v[64:79], v[64:67], v[68:71], 0
	v_perm_b32 v107, v106, v107, s39
	v_perm_b32 v106, v104, v105, s39
	v_perm_b32 v105, v102, v103, s39
	v_perm_b32 v104, v100, v101, s39
	v_perm_b32 v103, v155, v156, s39
	v_perm_b32 v102, v153, v154, s39
	v_perm_b32 v101, v151, v152, s39
	s_waitcnt lgkmcnt(0)
	v_mfma_f32_32x32x16_bf16 v[64:79], v[168:171], v[172:175], v[64:79]
	ds_read2_b64 v[168:171], v112 offset0:8 offset1:10
	v_cvt_pk_bf16_f32 v172, v32, v33
	v_cvt_pk_bf16_f32 v173, v34, v35
	v_cvt_pk_bf16_f32 v174, v36, v37
	v_cvt_pk_bf16_f32 v175, v38, v39
	v_perm_b32 v100, v114, v150, s39
	v_cmp_gt_u32_e32 vcc, 4, v166
	s_waitcnt lgkmcnt(0)
	v_mfma_f32_32x32x16_bf16 v[80:95], v[168:171], v[172:175], v[80:95]
	ds_read2_b64 v[168:171], v176 offset0:72 offset1:74
	s_waitcnt lgkmcnt(0)
	v_mfma_f32_32x32x16_bf16 v[64:79], v[168:171], v[172:175], v[64:79]
	ds_read2_b64 v[168:171], v112 offset0:12 offset1:14
	v_cvt_pk_bf16_f32 v172, v40, v41
	v_cvt_pk_bf16_f32 v173, v42, v43
	v_cvt_pk_bf16_f32 v174, v44, v45
	v_cvt_pk_bf16_f32 v175, v46, v47
	s_waitcnt lgkmcnt(0)
	s_nop 0
	v_mfma_f32_32x32x16_bf16 v[80:95], v[168:171], v[172:175], v[80:95]
	ds_read2_b64 v[168:171], v176 offset0:76 offset1:78
	s_waitcnt lgkmcnt(0)
	v_mfma_f32_32x32x16_bf16 v[64:79], v[168:171], v[172:175], v[64:79]
	ds_read2_b64 v[168:171], v112 offset0:16 offset1:18
	v_cvt_pk_bf16_f32 v172, v16, v17
	v_cvt_pk_bf16_f32 v173, v18, v19
	v_cvt_pk_bf16_f32 v174, v20, v21
	v_cvt_pk_bf16_f32 v175, v22, v23
	s_waitcnt lgkmcnt(0)
	s_nop 0
	v_mfma_f32_32x32x16_bf16 v[80:95], v[168:171], v[172:175], v[80:95]
	ds_read2_b64 v[168:171], v176 offset0:80 offset1:82
	s_waitcnt lgkmcnt(0)
	v_mfma_f32_32x32x16_bf16 v[64:79], v[168:171], v[172:175], v[64:79]
	ds_read2_b64 v[168:171], v112 offset0:20 offset1:22
	v_cvt_pk_bf16_f32 v172, v24, v25
	v_cvt_pk_bf16_f32 v173, v26, v27
	v_cvt_pk_bf16_f32 v174, v28, v29
	v_cvt_pk_bf16_f32 v175, v30, v31
	s_waitcnt lgkmcnt(0)
	s_nop 0
	v_mfma_f32_32x32x16_bf16 v[80:95], v[168:171], v[172:175], v[80:95]
	ds_read2_b64 v[168:171], v176 offset0:84 offset1:86
	s_waitcnt lgkmcnt(0)
	v_mfma_f32_32x32x16_bf16 v[64:79], v[168:171], v[172:175], v[64:79]
	ds_read2_b64 v[168:171], v112 offset0:24 offset1:26
	v_cvt_pk_bf16_f32 v172, v0, v1
	v_cvt_pk_bf16_f32 v173, v2, v3
	v_cvt_pk_bf16_f32 v174, v4, v5
	v_cvt_pk_bf16_f32 v175, v6, v7
	s_waitcnt lgkmcnt(0)
	s_nop 0
	v_mfma_f32_32x32x16_bf16 v[80:95], v[168:171], v[172:175], v[80:95]
	ds_read2_b64 v[168:171], v176 offset0:88 offset1:90
	ds_read2_b64 v[176:179], v176 offset0:92 offset1:94
	s_waitcnt lgkmcnt(1)
	v_mfma_f32_32x32x16_bf16 v[64:79], v[168:171], v[172:175], v[64:79]
	ds_read2_b64 v[168:171], v112 offset0:28 offset1:30
	v_cvt_pk_bf16_f32 v172, v8, v9
	v_cvt_pk_bf16_f32 v173, v10, v11
	v_cvt_pk_bf16_f32 v174, v12, v13
	v_cvt_pk_bf16_f32 v175, v14, v15
	s_waitcnt lgkmcnt(0)
	s_nop 0
	v_mfma_f32_32x32x16_bf16 v[80:95], v[168:171], v[172:175], v[80:95]
	v_add_u32_e32 v169, s14, v167
	v_mul_u32_u24_e32 v168, 0x90, v165
	ds_read_b128 v[182:185], v169 offset:512
	ds_read_b128 v[186:189], v169 offset:544
	v_add3_u32 v112, s38, v167, v168
	s_waitcnt lgkmcnt(0)
	s_nop 5
	v_pk_mul_f32 v[86:87], v[86:87], v[188:189]
	v_mfma_f32_32x32x16_bf16 v[64:79], v[176:179], v[172:175], v[64:79]
	ds_read_b128 v[170:173], v169 offset:576
	ds_read_b128 v[174:177], v169 offset:608
	ds_read_b128 v[190:193], v169 offset:640
	ds_read_b128 v[194:197], v169 offset:672
	ds_read_b128 v[198:201], v169 offset:704
	ds_read_b128 v[202:205], v169 offset:736
	s_waitcnt lgkmcnt(0)
	s_barrier
	ds_read_b128 v[108:111], v112
	s_waitcnt lgkmcnt(5)
	v_pk_mul_f32 v[94:95], v[94:95], v[176:177]
	v_pk_mul_f32 v[92:93], v[92:93], v[174:175]
	v_pk_mul_f32 v[90:91], v[90:91], v[172:173]
	v_pk_mul_f32 v[88:89], v[88:89], v[170:171]
	v_pk_mul_f32 v[84:85], v[84:85], v[186:187]
	v_pk_mul_f32 v[82:83], v[82:83], v[184:185]
	v_pk_mul_f32 v[80:81], v[80:81], v[182:183]
	ds_read_b128 v[170:173], v112 offset:32
	s_waitcnt lgkmcnt(2)
	v_pk_mul_f32 v[78:79], v[78:79], v[204:205]
	s_waitcnt lgkmcnt(1)
	v_mfma_f32_32x32x16_bf16 v[80:95], v[108:111], v[96:99], v[80:95]
	ds_read_b128 v[108:111], v112 offset:4608
	ds_read_b128 v[174:177], v112 offset:4640
	v_mul_f32_e64 v76, v76, v202
	v_mul_f32_e64 v77, v77, v203
	v_mul_f32_e64 v74, v74, v200
	v_mul_f32_e64 v75, v75, v201
	v_pk_mul_f32 v[72:73], v[72:73], v[198:199]
	v_pk_mul_f32 v[70:71], v[70:71], v[196:197]
	v_pk_mul_f32 v[68:69], v[68:69], v[194:195]
	v_pk_mul_f32 v[66:67], v[66:67], v[192:193]
	v_pk_mul_f32 v[64:65], v[64:65], v[190:191]
	s_waitcnt lgkmcnt(2)
	v_mfma_f32_32x32x16_bf16 v[80:95], v[170:173], v[104:107], v[80:95]
	ds_read_b128 v[150:153], v112 offset:96
	s_waitcnt lgkmcnt(2)
	v_mfma_f32_32x32x16_bf16 v[64:79], v[108:111], v[96:99], v[64:79]
	ds_read_b128 v[108:111], v112 offset:64
	s_waitcnt lgkmcnt(2)
	v_mfma_f32_32x32x16_bf16 v[64:79], v[174:177], v[104:107], v[64:79]
	s_waitcnt lgkmcnt(0)
	v_mfma_f32_32x32x16_bf16 v[80:95], v[108:111], v[100:103], v[80:95]
	ds_read_b128 v[108:111], v112 offset:4672
	ds_read_b128 v[170:173], v112 offset:4704
	s_waitcnt lgkmcnt(0)
	s_barrier
; DI bf16_t f2bf(float a) { return (bf16_t)(pk2(a, 0.f) & 0xffffu); }
; #define MFMA32(a, b, c) __builtin_amdgcn_mfma_f32_32x32x16_bf16((a), (b), (c), 0, 0, 0)
; DI int crow(int reg, int hh) { return (reg & 3) + 8 * (reg >> 2) + 4 * hh; }
; #define LDS_BARRIER() do { asm volatile("s_waitcnt lgkmcnt(0)" ::: "memory"); __builtin_amdgcn_s_barrier(); asm volatile("" ::: "memory"); } while (0)
; template <bool CONS>
; DI void ml_chain_role(const Params& p, unsigned char* smem, int dir, int b, int h) {
;     ...
;                     for (int mi = 0; mi < 2; ++mi) o[mi] = MFMA32(load_nat(sS, STT, 32 * mi + r, 32 * ci + 16 * s + 8 * hh), vf[ci][s], o[mi]);
;         }
;         LDS_BARRIER();
;         const float cs = sCs[0];
;         if (CONS) {
;             __builtin_amdgcn_s_setprio(2);
;             if (seg) {
; #pragma unroll
;                 for (int mi = 0; mi < 2; ++mi)
; #pragma unroll
;                     for (int i = 0; i < 16; ++i) { const int il = 32 * mi + crow(i, hh); const unsigned off = (unsigned)sRow[il] * 1024u + (unsigned)(512 + h * 128 + 32 * wave + r);
;                         O[off] = f2bf(o[mi][i] * sRden[il]); }
;             }
	v_mov_b32_e32 v112, s14
	ds_read_b32 v114, v112 offset:2304
	s_waitcnt lgkmcnt(2)
	v_mfma_f32_32x32x16_bf16 v[64:79], v[108:111], v[100:103], v[64:79]
	v_perm_b32 v111, v163, v164, s39
	v_perm_b32 v110, v161, v162, s39
	v_perm_b32 v109, v159, v160, s39
	v_perm_b32 v108, v157, v158, s39
	s_nop 1
	v_mfma_f32_32x32x16_bf16 v[80:95], v[150:153], v[108:111], v[80:95]
	s_waitcnt lgkmcnt(1)
	v_mfma_f32_32x32x16_bf16 v[64:79], v[170:173], v[108:111], v[64:79]
	s_setprio 2
	s_mov_b32 s86, 0
	s_cbranch_vccnz .LBB0_479
	s_mov_b32 s86, 1
	ds_read_b128 v[150:153], v169 offset:1280
	ds_read_b128 v[154:157], v169 offset:1312
	ds_read_b128 v[158:161], v169 offset:1536
	v_or_b32_e32 v166, s24, v165
	ds_read_b128 v[162:165], v169 offset:1568
	s_waitcnt lgkmcnt(3)
	s_nop 1
	v_mul_f32_e32 v80, v80, v150
	v_mul_f32_e32 v81, v81, v151
	v_cvt_pk_bf16_f32 v170, v80, s0
	v_cvt_pk_bf16_f32 v171, v81, s0
	s_waitcnt lgkmcnt(1)
	v_lshl_add_u32 v80, v159, 10, v166
	v_lshl_add_u32 v112, v158, 10, v166
	v_mov_b32_e32 v81, v113
	v_lshl_add_u64 v[150:151], v[112:113], 1, s[12:13]
	v_lshl_add_u64 v[80:81], v[80:81], 1, s[12:13]
	global_store_short v[150:151], v170, off
	global_store_short v[80:81], v171, off
	v_mul_f32_e32 v80, v82, v152
	v_lshl_add_u32 v112, v160, 10, v166
	v_cvt_pk_bf16_f32 v81, v80, s0
	v_mul_f32_e32 v80, v83, v153
	v_lshl_add_u64 v[82:83], v[112:113], 1, s[12:13]
	v_cvt_pk_bf16_f32 v150, v80, s0
	v_lshl_add_u32 v80, v161, 10, v166
	global_store_short v[82:83], v81, off
	v_mov_b32_e32 v81, v113
	v_lshl_add_u64 v[80:81], v[80:81], 1, s[12:13]
	global_store_short v[80:81], v150, off
	v_mul_f32_e32 v80, v84, v154
	ds_read_b128 v[150:153], v169 offset:1600
	s_waitcnt lgkmcnt(1)
	v_lshl_add_u32 v112, v162, 10, v166
	v_cvt_pk_bf16_f32 v81, v80, s0
	v_mul_f32_e32 v80, v85, v155
	v_lshl_add_u64 v[82:83], v[112:113], 1, s[12:13]
	v_cvt_pk_bf16_f32 v84, v80, s0
	v_lshl_add_u32 v80, v163, 10, v166
	global_store_short v[82:83], v81, off
	v_mov_b32_e32 v81, v113
	v_lshl_add_u64 v[80:81], v[80:81], 1, s[12:13]
	global_store_short v[80:81], v84, off
	v_mul_f32_e32 v80, v86, v156
	v_cvt_pk_bf16_f32 v82, v80, s0
	v_mul_f32_e32 v80, v87, v157
	v_lshl_add_u32 v112, v164, 10, v166
	v_cvt_pk_bf16_f32 v86, v80, s0
	v_lshl_add_u64 v[80:81], v[112:113], 1, s[12:13]
	global_store_short v[80:81], v82, off
	ds_read_b128 v[80:83], v169 offset:1344
	v_lshl_add_u32 v84, v165, 10, v166
	v_mov_b32_e32 v85, v113
	v_lshl_add_u64 v[84:85], v[84:85], 1, s[12:13]
	global_store_short v[84:85], v86, off
	ds_read_b128 v[84:87], v169 offset:1376
	s_waitcnt lgkmcnt(1)
	v_mul_f32_e32 v80, v88, v80
	v_cvt_pk_bf16_f32 v158, v80, s0
	v_mul_f32_e32 v80, v89, v81
	v_cvt_pk_bf16_f32 v159, v80, s0
	v_lshl_add_u32 v80, v151, 10, v166
	v_lshl_add_u32 v112, v150, 10, v166
	v_mov_b32_e32 v81, v113
	ds_read_b128 v[154:157], v169 offset:1632
	v_lshl_add_u64 v[88:89], v[112:113], 1, s[12:13]
	v_lshl_add_u64 v[80:81], v[80:81], 1, s[12:13]
	global_store_short v[88:89], v158, off
	global_store_short v[80:81], v159, off
	v_mul_f32_e32 v80, v90, v82
	v_lshl_add_u32 v112, v152, 10, v166
	v_cvt_pk_bf16_f32 v81, v80, s0
	v_mul_f32_e32 v80, v91, v83
	v_lshl_add_u64 v[82:83], v[112:113], 1, s[12:13]
	v_cvt_pk_bf16_f32 v88, v80, s0
	v_lshl_add_u32 v80, v153, 10, v166
	global_store_short v[82:83], v81, off
	v_mov_b32_e32 v81, v113
	v_lshl_add_u64 v[80:81], v[80:81], 1, s[12:13]
	global_store_short v[80:81], v88, off
	s_waitcnt lgkmcnt(1)
	v_mul_f32_e32 v80, v92, v84
	ds_read_b128 v[88:91], v169 offset:1664
	s_waitcnt lgkmcnt(1)
; DI bf16_t f2bf(float a) { return (bf16_t)(pk2(a, 0.f) & 0xffffu); }
; DI int crow(int reg, int hh) { return (reg & 3) + 8 * (reg >> 2) + 4 * hh; }
; template <bool CONS>
; DI void ml_chain_role(const Params& p, unsigned char* smem, int dir, int b, int h) {
;     ...
;             if (seg) {
; #pragma unroll
;                 for (int mi = 0; mi < 2; ++mi)
; #pragma unroll
;                     for (int i = 0; i < 16; ++i) { const int il = 32 * mi + crow(i, hh); const unsigned off = (unsigned)sRow[il] * 1024u + (unsigned)(512 + h * 128 + 32 * wave + r);
;                         O[off] = f2bf(o[mi][i] * sRden[il]); }
;             }
	v_lshl_add_u32 v112, v154, 10, v166
	v_cvt_pk_bf16_f32 v81, v80, s0
	v_mul_f32_e32 v80, v93, v85
	v_lshl_add_u64 v[82:83], v[112:113], 1, s[12:13]
	v_cvt_pk_bf16_f32 v84, v80, s0
	v_lshl_add_u32 v80, v155, 10, v166
	global_store_short v[82:83], v81, off
	v_mov_b32_e32 v81, v113
	v_lshl_add_u64 v[80:81], v[80:81], 1, s[12:13]
	global_store_short v[80:81], v84, off
	v_mul_f32_e32 v80, v94, v86
	v_cvt_pk_bf16_f32 v82, v80, s0
	v_mul_f32_e32 v80, v95, v87
	v_lshl_add_u32 v112, v156, 10, v166
	v_cvt_pk_bf16_f32 v86, v80, s0
	v_lshl_add_u64 v[80:81], v[112:113], 1, s[12:13]
	global_store_short v[80:81], v82, off
	ds_read_b128 v[80:83], v169 offset:1408
	v_lshl_add_u32 v84, v157, 10, v166
	v_mov_b32_e32 v85, v113
	v_lshl_add_u64 v[84:85], v[84:85], 1, s[12:13]
	global_store_short v[84:85], v86, off
	ds_read_b128 v[84:87], v169 offset:1440
	s_waitcnt lgkmcnt(1)
	v_mul_f32_e32 v64, v64, v80
	v_cvt_pk_bf16_f32 v150, v64, s0
	v_mul_f32_e32 v64, v65, v81
	v_cvt_pk_bf16_f32 v151, v64, s0
	v_lshl_add_u32 v64, v89, 10, v166
	v_lshl_add_u32 v112, v88, 10, v166
	v_mov_b32_e32 v65, v113
	ds_read_b128 v[92:95], v169 offset:1696
	v_lshl_add_u64 v[80:81], v[112:113], 1, s[12:13]
	v_lshl_add_u64 v[64:65], v[64:65], 1, s[12:13]
	global_store_short v[80:81], v150, off
	global_store_short v[64:65], v151, off
	v_mul_f32_e32 v64, v66, v82
	v_lshl_add_u32 v112, v90, 10, v166
	v_cvt_pk_bf16_f32 v65, v64, s0
	v_mul_f32_e32 v64, v67, v83
	v_lshl_add_u64 v[66:67], v[112:113], 1, s[12:13]
	v_cvt_pk_bf16_f32 v80, v64, s0
	v_lshl_add_u32 v64, v91, 10, v166
	global_store_short v[66:67], v65, off
	v_mov_b32_e32 v65, v113
	v_lshl_add_u64 v[64:65], v[64:65], 1, s[12:13]
	global_store_short v[64:65], v80, off
	s_waitcnt lgkmcnt(1)
	v_mul_f32_e32 v64, v68, v84
	ds_read_b128 v[80:83], v169 offset:1728
	s_waitcnt lgkmcnt(1)
	v_lshl_add_u32 v112, v92, 10, v166
	v_cvt_pk_bf16_f32 v65, v64, s0
	v_mul_f32_e32 v64, v69, v85
	v_lshl_add_u64 v[66:67], v[112:113], 1, s[12:13]
	v_cvt_pk_bf16_f32 v68, v64, s0
	v_lshl_add_u32 v64, v93, 10, v166
	global_store_short v[66:67], v65, off
	v_mov_b32_e32 v65, v113
	v_lshl_add_u64 v[64:65], v[64:65], 1, s[12:13]
	global_store_short v[64:65], v68, off
	v_mul_f32_e32 v64, v70, v86
	v_cvt_pk_bf16_f32 v66, v64, s0
	v_mul_f32_e32 v64, v71, v87
	v_lshl_add_u32 v112, v94, 10, v166
	v_cvt_pk_bf16_f32 v70, v64, s0
	v_lshl_add_u64 v[64:65], v[112:113], 1, s[12:13]
	global_store_short v[64:65], v66, off
	ds_read_b128 v[64:67], v169 offset:1472
	v_lshl_add_u32 v68, v95, 10, v166
	v_mov_b32_e32 v69, v113
	v_lshl_add_u64 v[68:69], v[68:69], 1, s[12:13]
	global_store_short v[68:69], v70, off
	ds_read_b128 v[68:71], v169 offset:1504
	s_waitcnt lgkmcnt(1)
	v_mul_f32_e32 v64, v72, v64
	v_cvt_pk_bf16_f32 v88, v64, s0
	v_mul_f32_e32 v64, v73, v65
	v_cvt_pk_bf16_f32 v89, v64, s0
	v_lshl_add_u32 v64, v81, 10, v166
	v_lshl_add_u32 v112, v80, 10, v166
	v_mov_b32_e32 v65, v113
	ds_read_b128 v[84:87], v169 offset:1760
	v_lshl_add_u64 v[72:73], v[112:113], 1, s[12:13]
	v_lshl_add_u64 v[64:65], v[64:65], 1, s[12:13]
	global_store_short v[72:73], v88, off
	global_store_short v[64:65], v89, off
	v_mul_f32_e32 v64, v74, v66
	v_lshl_add_u32 v112, v82, 10, v166
	v_cvt_pk_bf16_f32 v65, v64, s0
	v_mul_f32_e32 v64, v75, v67
	v_lshl_add_u64 v[66:67], v[112:113], 1, s[12:13]
	v_cvt_pk_bf16_f32 v72, v64, s0
	v_lshl_add_u32 v64, v83, 10, v166
	global_store_short v[66:67], v65, off
	v_mov_b32_e32 v65, v113
	v_lshl_add_u64 v[64:65], v[64:65], 1, s[12:13]
	global_store_short v[64:65], v72, off
	s_waitcnt lgkmcnt(1)
	v_mul_f32_e32 v64, v76, v68
	s_waitcnt lgkmcnt(0)
	v_lshl_add_u32 v112, v84, 10, v166
	v_cvt_pk_bf16_f32 v65, v64, s0
	v_mul_f32_e32 v64, v77, v69
	v_lshl_add_u64 v[66:67], v[112:113], 1, s[12:13]
	v_cvt_pk_bf16_f32 v68, v64, s0
	v_lshl_add_u32 v64, v85, 10, v166
	global_store_short v[66:67], v65, off
	v_mov_b32_e32 v65, v113
	v_lshl_add_u64 v[64:65], v[64:65], 1, s[12:13]
	global_store_short v[64:65], v68, off
	v_mul_f32_e32 v64, v78, v70
	v_lshl_add_u32 v112, v86, 10, v166
	v_cvt_pk_bf16_f32 v65, v64, s0
	v_mul_f32_e32 v64, v79, v71
	v_lshl_add_u64 v[66:67], v[112:113], 1, s[12:13]
	v_cvt_pk_bf16_f32 v68, v64, s0
	v_lshl_add_u32 v64, v87, 10, v166
	global_store_short v[66:67], v65, off
	v_mov_b32_e32 v65, v113
	v_lshl_add_u64 v[64:65], v[64:65], 1, s[12:13]
	global_store_short v[64:65], v68, off
	s_branch .LBB0_479
